# gate stores nt sc1 + rows-phase row loads nt + weight-transpose f32 loads nt + no entry grid.sync
# speedup vs baseline: 1.0154x; 1.0004x over previous
; __device__ __forceinline__ unsigned pk_bf16(float lo, float hi) { return pg8::cvt_pk_bf16(lo, hi); }
; #define LDS_FENCE() asm volatile("s_waitcnt lgkmcnt(0)" ::: "memory")
; __device__ __forceinline__ void transpose_item(const float* Wsrc, int ldw, bf16_t* WT, int ldt, int kb, int nb, float* scr, int lane) {
;     const int k0 = 64 * kb, n0 = 32 * nb;
; #pragma unroll
;     for (int i = 0; i < 8; ++i) { const int kk = 8 * i + (lane >> 3), n4 = 4 * (lane & 7);
;         const f32x4 v = *(const f32x4*)(Wsrc + (size_t)(k0 + kk) * ldw + n0 + n4);
;         scr[kk * 33 + n4] = v[0]; scr[kk * 33 + n4 + 1] = v[1]; scr[kk * 33 + n4 + 2] = v[2]; scr[kk * 33 + n4 + 3] = v[3]; }
;     LDS_FENCE();
;     const int c = lane & 7;
; #pragma unroll
;     for (int j = 0; j < 4; ++j) { const int n = (lane >> 3) + 8 * j; const float* s = scr + (8 * c) * 33 + n;
;         u32x4 o; o.x = pk_bf16(s[0 * 33], s[1 * 33]); o.y = pk_bf16(s[2 * 33], s[3 * 33]); o.z = pk_bf16(s[4 * 33], s[5 * 33]); o.w = pk_bf16(s[6 * 33], s[7 * 33]);
;         *(u32x4*)(WT + (size_t)(n0 + n) * ldt + k0 + 8 * c) = o; }
;     LDS_FENCE();
; }
; __device__ __forceinline__ void phase_rows(const Ctx& c, int l) {
;     ...
;             transpose_item(c.inp(IN_WGLU) + (size_t)l * 256 * 256, 256, Wglu_t, 256, r / 8, r % 8, scr, lane);
.LBB0_459:
	s_cmpk_gt_i32 s23, 0xbff
	s_mov_b64 s[52:53], -1
	s_cbranch_scc0 .LBB0_477
	s_cmpk_gt_u32 s23, 0xc7f
	s_cbranch_scc0 .LBB0_474
	s_cmpk_gt_u32 s23, 0xd7f
	s_cbranch_scc0 .LBB0_471
	s_cmpk_gt_u32 s23, 0xdff
	s_cbranch_scc0 .LBB0_468
	s_cmpk_gt_u32 s23, 0xfff
	s_cbranch_scc0 .LBB0_465
	s_load_dwordx2 s[52:53], s[50:51], 0x68
	v_lshlrev_b32_e32 v96, 2, v4
	s_waitcnt lgkmcnt(0)
	s_add_u32 s31, s52, s38
	s_addc_u32 s36, s53, s39
	s_and_b32 s6, s17, 0x7fffffc0
	s_add_i32 s34, s6, 0xffff8000
	s_and_b32 s6, s13, 0xe0
	s_lshl_b32 s47, s6, 2
	s_add_u32 s52, s31, s47
	s_addc_u32 s53, s36, 0
	v_lshl_add_u64 v[18:19], s[52:53], 0, v[96:97]
	v_or_b32_e32 v96, s34, v20
	v_lshlrev_b64 v[0:1], 10, v[96:97]
	v_lshl_add_u64 v[0:1], v[18:19], 0, v[0:1]
	global_load_dwordx4 v[0:3], v[0:1], off nt
	v_or_b32_e32 v96, s34, v22
	v_or_b32_e32 v37, s6, v20
	s_mov_b64 s[52:53], 0
	s_waitcnt vmcnt(0)
	ds_write2_b32 v21, v0, v1 offset1:1
	ds_write2_b32 v21, v2, v3 offset0:2 offset1:3
	v_lshlrev_b64 v[0:1], 10, v[96:97]
	v_lshl_add_u64 v[0:1], v[18:19], 0, v[0:1]
	global_load_dwordx4 v[0:3], v[0:1], off nt
	v_or_b32_e32 v96, s34, v24
	s_waitcnt vmcnt(0)
	ds_write2_b32 v23, v0, v1 offset1:1
	ds_write2_b32 v23, v2, v3 offset0:2 offset1:3
	v_lshlrev_b64 v[0:1], 10, v[96:97]
	v_lshl_add_u64 v[0:1], v[18:19], 0, v[0:1]
	global_load_dwordx4 v[0:3], v[0:1], off nt
	v_or_b32_e32 v96, s34, v26
	s_waitcnt vmcnt(0)
	ds_write2_b32 v25, v0, v1 offset1:1
	ds_write2_b32 v25, v2, v3 offset0:2 offset1:3
	v_lshlrev_b64 v[0:1], 10, v[96:97]
	v_lshl_add_u64 v[0:1], v[18:19], 0, v[0:1]
	global_load_dwordx4 v[0:3], v[0:1], off nt
	v_or_b32_e32 v96, s34, v28
	s_waitcnt vmcnt(0)
	ds_write2_b32 v27, v0, v1 offset1:1
	ds_write2_b32 v27, v2, v3 offset0:2 offset1:3
	v_lshlrev_b64 v[0:1], 10, v[96:97]
	v_lshl_add_u64 v[0:1], v[18:19], 0, v[0:1]
	global_load_dwordx4 v[0:3], v[0:1], off nt
	v_or_b32_e32 v96, s34, v30
	s_waitcnt vmcnt(0)
	ds_write2_b32 v29, v0, v1 offset1:1
	ds_write2_b32 v29, v2, v3 offset0:2 offset1:3
	v_lshlrev_b64 v[0:1], 10, v[96:97]
	v_lshl_add_u64 v[0:1], v[18:19], 0, v[0:1]
	global_load_dwordx4 v[0:3], v[0:1], off nt
	v_or_b32_e32 v96, s34, v32
	s_waitcnt vmcnt(0)
	ds_write2_b32 v31, v0, v1 offset1:1
	ds_write2_b32 v31, v2, v3 offset0:2 offset1:3
	v_lshlrev_b64 v[0:1], 10, v[96:97]
	v_lshl_add_u64 v[0:1], v[18:19], 0, v[0:1]
	global_load_dwordx4 v[0:3], v[0:1], off nt
	v_or_b32_e32 v96, s34, v34
	s_waitcnt vmcnt(0)
	ds_write2_b32 v33, v0, v1 offset1:1
	ds_write2_b32 v33, v2, v3 offset0:2 offset1:3
	v_lshlrev_b64 v[0:1], 10, v[96:97]
	v_lshl_add_u64 v[0:1], v[18:19], 0, v[0:1]
	global_load_dwordx4 v[0:3], v[0:1], off nt
	v_lshl_add_u64 v[18:19], s[34:35], 1, v[6:7]
	v_lshlrev_b32_e32 v96, 9, v37
	v_or_b32_e32 v37, s6, v22
	v_lshl_add_u64 v[54:55], v[18:19], 0, v[96:97]
	v_lshlrev_b32_e32 v96, 9, v37
	v_or_b32_e32 v37, s6, v24
	s_waitcnt vmcnt(0)
	ds_write2_b32 v35, v0, v1 offset1:1
	ds_write2_b32 v35, v2, v3 offset0:2 offset1:3
	s_waitcnt lgkmcnt(0)
	ds_read2_b32 v[38:39], v36 offset0:33 offset1:41
	ds_read2_b32 v[40:41], v36 offset1:8
	ds_read2_b32 v[42:43], v36 offset0:66 offset1:74
	ds_read2_b32 v[44:45], v36 offset0:99 offset1:107
	ds_read2_b32 v[46:47], v36 offset0:132 offset1:140
	ds_read2_b32 v[48:49], v36 offset0:165 offset1:173
	ds_read2_b32 v[50:51], v36 offset0:198 offset1:206
	ds_read2_b32 v[52:53], v36 offset0:231 offset1:239
	s_waitcnt lgkmcnt(6)
	v_cvt_pk_bf16_f32 v0, v40, v38
	s_waitcnt lgkmcnt(4)
	v_cvt_pk_bf16_f32 v1, v42, v44
	s_waitcnt lgkmcnt(2)
	v_cvt_pk_bf16_f32 v2, v46, v48
	s_waitcnt lgkmcnt(0)
	v_cvt_pk_bf16_f32 v3, v50, v52
	global_store_dwordx4 v[54:55], v[0:3], off
	s_nop 1
	v_cvt_pk_bf16_f32 v0, v41, v39
	v_cvt_pk_bf16_f32 v1, v43, v45
	v_cvt_pk_bf16_f32 v2, v47, v49
	v_cvt_pk_bf16_f32 v3, v51, v53
	v_lshl_add_u64 v[38:39], v[18:19], 0, v[96:97]
	global_store_dwordx4 v[38:39], v[0:3], off
	ds_read2_b32 v[38:39], v36 offset0:49 offset1:57
	ds_read2_b32 v[40:41], v36 offset0:16 offset1:24
	ds_read2_b32 v[42:43], v36 offset0:82 offset1:90
	ds_read2_b32 v[44:45], v36 offset0:115 offset1:123
	ds_read2_b32 v[46:47], v36 offset0:148 offset1:156
	ds_read2_b32 v[48:49], v36 offset0:181 offset1:189
	ds_read2_b32 v[50:51], v36 offset0:214 offset1:222
	ds_read2_b32 v[52:53], v36 offset0:247 offset1:255
	v_lshlrev_b32_e32 v96, 9, v37
	v_or_b32_e32 v37, s6, v26
	s_waitcnt lgkmcnt(6)
	v_cvt_pk_bf16_f32 v0, v40, v38
	s_waitcnt lgkmcnt(4)
	v_cvt_pk_bf16_f32 v1, v42, v44
	s_waitcnt lgkmcnt(2)
	v_cvt_pk_bf16_f32 v2, v46, v48
	s_waitcnt lgkmcnt(0)
	v_cvt_pk_bf16_f32 v3, v50, v52
	v_lshl_add_u64 v[54:55], v[18:19], 0, v[96:97]
	v_lshlrev_b32_e32 v96, 9, v37
	global_store_dwordx4 v[54:55], v[0:3], off
	v_lshl_add_u64 v[18:19], v[18:19], 0, v[96:97]
	s_nop 0
	v_cvt_pk_bf16_f32 v0, v41, v39
	v_cvt_pk_bf16_f32 v1, v43, v45
	v_cvt_pk_bf16_f32 v2, v47, v49
	v_cvt_pk_bf16_f32 v3, v51, v53
	global_store_dwordx4 v[18:19], v[0:3], off
	s_waitcnt lgkmcnt(0)
; __device__ __forceinline__ unsigned pk_bf16(float lo, float hi) { return pg8::cvt_pk_bf16(lo, hi); }
; #define LDS_FENCE() asm volatile("s_waitcnt lgkmcnt(0)" ::: "memory")
; __device__ __forceinline__ void transpose_item(const float* Wsrc, int ldw, bf16_t* WT, int ldt, int kb, int nb, float* scr, int lane) {
;     const int k0 = 64 * kb, n0 = 32 * nb;
; #pragma unroll
;     for (int i = 0; i < 8; ++i) { const int kk = 8 * i + (lane >> 3), n4 = 4 * (lane & 7);
;         const f32x4 v = *(const f32x4*)(Wsrc + (size_t)(k0 + kk) * ldw + n0 + n4);
;         scr[kk * 33 + n4] = v[0]; scr[kk * 33 + n4 + 1] = v[1]; scr[kk * 33 + n4 + 2] = v[2]; scr[kk * 33 + n4 + 3] = v[3]; }
;     LDS_FENCE();
;     const int c = lane & 7;
; #pragma unroll
;     for (int j = 0; j < 4; ++j) { const int n = (lane >> 3) + 8 * j; const float* s = scr + (8 * c) * 33 + n;
;         u32x4 o; o.x = pk_bf16(s[0 * 33], s[1 * 33]); o.y = pk_bf16(s[2 * 33], s[3 * 33]); o.z = pk_bf16(s[4 * 33], s[5 * 33]); o.w = pk_bf16(s[6 * 33], s[7 * 33]);
;         *(u32x4*)(WT + (size_t)(n0 + n) * ldt + k0 + 8 * c) = o; }
;     LDS_FENCE();
; }
; __device__ __forceinline__ void phase_rows(const Ctx& c, int l) {
;     ...
;             if (r < I_O) { transpose_item(c.inp(IN_WOUT) + (size_t)l * 1024 * 1024, 1024, Wout_t, 1024, r / 32, r % 32, scr, lane); continue; } r -= I_O;
.LBB0_465:
	s_andn2_b64 vcc, exec, s[52:53]
	s_cbranch_vccnz .LBB0_467
	s_load_dwordx2 s[52:53], s[50:51], 0x90
	v_lshlrev_b32_e32 v96, 2, v4
	s_waitcnt lgkmcnt(0)
	s_add_u32 s31, s52, s40
	s_addc_u32 s36, s53, s41
	s_and_b32 s6, s21, 0x1fc0
	s_add_i32 s34, s6, 0xffffe400
	s_and_b32 s6, s13, 0x3e0
	s_lshl_b32 s47, s6, 2
	s_add_u32 s52, s31, s47
	s_addc_u32 s53, s36, 0
	v_lshl_add_u64 v[18:19], s[52:53], 0, v[96:97]
	v_or_b32_e32 v96, s34, v20
	v_lshlrev_b64 v[0:1], 12, v[96:97]
	v_lshl_add_u64 v[0:1], v[18:19], 0, v[0:1]
	global_load_dwordx4 v[0:3], v[0:1], off nt
	v_or_b32_e32 v96, s34, v22
	v_or_b32_e32 v37, s6, v20
	s_waitcnt vmcnt(0)
	ds_write2_b32 v21, v0, v1 offset1:1
	ds_write2_b32 v21, v2, v3 offset0:2 offset1:3
	v_lshlrev_b64 v[0:1], 12, v[96:97]
	v_lshl_add_u64 v[0:1], v[18:19], 0, v[0:1]
	global_load_dwordx4 v[0:3], v[0:1], off nt
	v_or_b32_e32 v96, s34, v24
	s_waitcnt vmcnt(0)
	ds_write2_b32 v23, v0, v1 offset1:1
	ds_write2_b32 v23, v2, v3 offset0:2 offset1:3
	v_lshlrev_b64 v[0:1], 12, v[96:97]
	v_lshl_add_u64 v[0:1], v[18:19], 0, v[0:1]
	global_load_dwordx4 v[0:3], v[0:1], off nt
	v_or_b32_e32 v96, s34, v26
	s_waitcnt vmcnt(0)
	ds_write2_b32 v25, v0, v1 offset1:1
	ds_write2_b32 v25, v2, v3 offset0:2 offset1:3
	v_lshlrev_b64 v[0:1], 12, v[96:97]
	v_lshl_add_u64 v[0:1], v[18:19], 0, v[0:1]
	global_load_dwordx4 v[0:3], v[0:1], off nt
	v_or_b32_e32 v96, s34, v28
	s_waitcnt vmcnt(0)
	ds_write2_b32 v27, v0, v1 offset1:1
	ds_write2_b32 v27, v2, v3 offset0:2 offset1:3
	v_lshlrev_b64 v[0:1], 12, v[96:97]
	v_lshl_add_u64 v[0:1], v[18:19], 0, v[0:1]
	global_load_dwordx4 v[0:3], v[0:1], off nt
	v_or_b32_e32 v96, s34, v30
	s_waitcnt vmcnt(0)
	ds_write2_b32 v29, v0, v1 offset1:1
	ds_write2_b32 v29, v2, v3 offset0:2 offset1:3
	v_lshlrev_b64 v[0:1], 12, v[96:97]
	v_lshl_add_u64 v[0:1], v[18:19], 0, v[0:1]
	global_load_dwordx4 v[0:3], v[0:1], off nt
	v_or_b32_e32 v96, s34, v32
	s_waitcnt vmcnt(0)
	ds_write2_b32 v31, v0, v1 offset1:1
	ds_write2_b32 v31, v2, v3 offset0:2 offset1:3
	v_lshlrev_b64 v[0:1], 12, v[96:97]
	v_lshl_add_u64 v[0:1], v[18:19], 0, v[0:1]
	global_load_dwordx4 v[0:3], v[0:1], off nt
	v_or_b32_e32 v96, s34, v34
	s_waitcnt vmcnt(0)
	ds_write2_b32 v33, v0, v1 offset1:1
	ds_write2_b32 v33, v2, v3 offset0:2 offset1:3
	v_lshlrev_b64 v[0:1], 12, v[96:97]
	v_lshl_add_u64 v[0:1], v[18:19], 0, v[0:1]
	global_load_dwordx4 v[0:3], v[0:1], off nt
	v_lshl_add_u64 v[18:19], s[34:35], 1, v[8:9]
	v_lshlrev_b32_e32 v96, 11, v37
	v_or_b32_e32 v37, s6, v22
	v_lshl_add_u64 v[54:55], v[18:19], 0, v[96:97]
	v_lshlrev_b32_e32 v96, 11, v37
	v_or_b32_e32 v37, s6, v24
	s_waitcnt vmcnt(0)
	ds_write2_b32 v35, v0, v1 offset1:1
	ds_write2_b32 v35, v2, v3 offset0:2 offset1:3
	s_waitcnt lgkmcnt(0)
	ds_read2_b32 v[38:39], v36 offset0:33 offset1:41
	ds_read2_b32 v[40:41], v36 offset1:8
	ds_read2_b32 v[42:43], v36 offset0:66 offset1:74
	ds_read2_b32 v[44:45], v36 offset0:99 offset1:107
	ds_read2_b32 v[46:47], v36 offset0:132 offset1:140
	ds_read2_b32 v[48:49], v36 offset0:165 offset1:173
	ds_read2_b32 v[50:51], v36 offset0:198 offset1:206
	ds_read2_b32 v[52:53], v36 offset0:231 offset1:239
	s_waitcnt lgkmcnt(6)
	v_cvt_pk_bf16_f32 v0, v40, v38
	s_waitcnt lgkmcnt(4)
	v_cvt_pk_bf16_f32 v1, v42, v44
	s_waitcnt lgkmcnt(2)
	v_cvt_pk_bf16_f32 v2, v46, v48
	s_waitcnt lgkmcnt(0)
	v_cvt_pk_bf16_f32 v3, v50, v52
	global_store_dwordx4 v[54:55], v[0:3], off
	s_nop 1
	v_cvt_pk_bf16_f32 v0, v41, v39
	v_cvt_pk_bf16_f32 v1, v43, v45
	v_cvt_pk_bf16_f32 v2, v47, v49
	v_cvt_pk_bf16_f32 v3, v51, v53
	v_lshl_add_u64 v[38:39], v[18:19], 0, v[96:97]
	global_store_dwordx4 v[38:39], v[0:3], off
	ds_read2_b32 v[38:39], v36 offset0:49 offset1:57
	ds_read2_b32 v[40:41], v36 offset0:16 offset1:24
	ds_read2_b32 v[42:43], v36 offset0:82 offset1:90
	ds_read2_b32 v[44:45], v36 offset0:115 offset1:123
	ds_read2_b32 v[46:47], v36 offset0:148 offset1:156
	ds_read2_b32 v[48:49], v36 offset0:181 offset1:189
	ds_read2_b32 v[50:51], v36 offset0:214 offset1:222
	ds_read2_b32 v[52:53], v36 offset0:247 offset1:255
	v_lshlrev_b32_e32 v96, 11, v37
	v_or_b32_e32 v37, s6, v26
	s_waitcnt lgkmcnt(6)
	v_cvt_pk_bf16_f32 v0, v40, v38
	s_waitcnt lgkmcnt(4)
	v_cvt_pk_bf16_f32 v1, v42, v44
	s_waitcnt lgkmcnt(2)
	v_cvt_pk_bf16_f32 v2, v46, v48
	s_waitcnt lgkmcnt(0)
	v_cvt_pk_bf16_f32 v3, v50, v52
	v_lshl_add_u64 v[54:55], v[18:19], 0, v[96:97]
	v_lshlrev_b32_e32 v96, 11, v37
	global_store_dwordx4 v[54:55], v[0:3], off
	v_lshl_add_u64 v[18:19], v[18:19], 0, v[96:97]
	s_nop 0
	v_cvt_pk_bf16_f32 v0, v41, v39
	v_cvt_pk_bf16_f32 v1, v43, v45
	v_cvt_pk_bf16_f32 v2, v47, v49
	v_cvt_pk_bf16_f32 v3, v51, v53
	global_store_dwordx4 v[18:19], v[0:3], off
	s_waitcnt lgkmcnt(0)

; __device__ __forceinline__ unsigned pk_bf16(float lo, float hi) { return pg8::cvt_pk_bf16(lo, hi); }
; #define LDS_FENCE() asm volatile("s_waitcnt lgkmcnt(0)" ::: "memory")
; __device__ __forceinline__ void transpose_item(const float* Wsrc, int ldw, bf16_t* WT, int ldt, int kb, int nb, float* scr, int lane) {
;     const int k0 = 64 * kb, n0 = 32 * nb;
; #pragma unroll
;     for (int i = 0; i < 8; ++i) { const int kk = 8 * i + (lane >> 3), n4 = 4 * (lane & 7);
;         const f32x4 v = *(const f32x4*)(Wsrc + (size_t)(k0 + kk) * ldw + n0 + n4);
;         scr[kk * 33 + n4] = v[0]; scr[kk * 33 + n4 + 1] = v[1]; scr[kk * 33 + n4 + 2] = v[2]; scr[kk * 33 + n4 + 3] = v[3]; }
;     LDS_FENCE();
;     const int c = lane & 7;
; #pragma unroll
;     for (int j = 0; j < 4; ++j) { const int n = (lane >> 3) + 8 * j; const float* s = scr + (8 * c) * 33 + n;
;         u32x4 o; o.x = pk_bf16(s[0 * 33], s[1 * 33]); o.y = pk_bf16(s[2 * 33], s[3 * 33]); o.z = pk_bf16(s[4 * 33], s[5 * 33]); o.w = pk_bf16(s[6 * 33], s[7 * 33]);
;         *(u32x4*)(WT + (size_t)(n0 + n) * ldt + k0 + 8 * c) = o; }
;     LDS_FENCE();
; }
; __device__ __forceinline__ void phase_rows(const Ctx& c, int l) {
;     ...
;             if (r < I_C) { transpose_item(c.inp(IN_WUPC) + (size_t)l * 256 * 1024, 1024, Wup_t + 768, 1024, r / 32, r % 32, scr, lane); continue; } r -= I_C;
.LBB0_468:
	s_andn2_b64 vcc, exec, s[52:53]
	s_cbranch_vccnz .LBB0_470
	s_load_dwordx2 s[52:53], s[50:51], 0x88
	v_lshlrev_b32_e32 v96, 2, v4
	s_waitcnt lgkmcnt(0)
	s_add_u32 s31, s52, s42
	s_addc_u32 s36, s53, s43
	s_and_b32 s6, s21, 0x1fc0
	s_add_i32 s34, s6, 0xffffe500
	s_and_b32 s6, s13, 0x3e0
	s_lshl_b32 s47, s6, 2
	s_add_u32 s52, s31, s47
	s_addc_u32 s53, s36, 0
	v_lshl_add_u64 v[18:19], s[52:53], 0, v[96:97]
	v_or_b32_e32 v96, s34, v20
	v_lshlrev_b64 v[0:1], 12, v[96:97]
	v_lshl_add_u64 v[0:1], v[18:19], 0, v[0:1]
	global_load_dwordx4 v[0:3], v[0:1], off nt
	v_or_b32_e32 v96, s34, v22
	v_or_b32_e32 v37, s6, v20
	s_waitcnt vmcnt(0)
	ds_write2_b32 v21, v0, v1 offset1:1
	ds_write2_b32 v21, v2, v3 offset0:2 offset1:3
	v_lshlrev_b64 v[0:1], 12, v[96:97]
	v_lshl_add_u64 v[0:1], v[18:19], 0, v[0:1]
	global_load_dwordx4 v[0:3], v[0:1], off nt
	v_or_b32_e32 v96, s34, v24
	s_waitcnt vmcnt(0)
	ds_write2_b32 v23, v0, v1 offset1:1
	ds_write2_b32 v23, v2, v3 offset0:2 offset1:3
	v_lshlrev_b64 v[0:1], 12, v[96:97]
	v_lshl_add_u64 v[0:1], v[18:19], 0, v[0:1]
	global_load_dwordx4 v[0:3], v[0:1], off nt
	v_or_b32_e32 v96, s34, v26
	s_waitcnt vmcnt(0)
	ds_write2_b32 v25, v0, v1 offset1:1
	ds_write2_b32 v25, v2, v3 offset0:2 offset1:3
	v_lshlrev_b64 v[0:1], 12, v[96:97]
	v_lshl_add_u64 v[0:1], v[18:19], 0, v[0:1]
	global_load_dwordx4 v[0:3], v[0:1], off nt
	v_or_b32_e32 v96, s34, v28
	s_waitcnt vmcnt(0)
	ds_write2_b32 v27, v0, v1 offset1:1
	ds_write2_b32 v27, v2, v3 offset0:2 offset1:3
	v_lshlrev_b64 v[0:1], 12, v[96:97]
	v_lshl_add_u64 v[0:1], v[18:19], 0, v[0:1]
	global_load_dwordx4 v[0:3], v[0:1], off nt
	v_or_b32_e32 v96, s34, v30
	s_waitcnt vmcnt(0)
	ds_write2_b32 v29, v0, v1 offset1:1
	ds_write2_b32 v29, v2, v3 offset0:2 offset1:3
	v_lshlrev_b64 v[0:1], 12, v[96:97]
	v_lshl_add_u64 v[0:1], v[18:19], 0, v[0:1]
	global_load_dwordx4 v[0:3], v[0:1], off nt
	v_or_b32_e32 v96, s34, v32
	s_waitcnt vmcnt(0)
	ds_write2_b32 v31, v0, v1 offset1:1
	ds_write2_b32 v31, v2, v3 offset0:2 offset1:3
	v_lshlrev_b64 v[0:1], 12, v[96:97]
	v_lshl_add_u64 v[0:1], v[18:19], 0, v[0:1]
	global_load_dwordx4 v[0:3], v[0:1], off nt
	v_or_b32_e32 v96, s34, v34
	s_waitcnt vmcnt(0)
	ds_write2_b32 v33, v0, v1 offset1:1
	ds_write2_b32 v33, v2, v3 offset0:2 offset1:3
	v_lshlrev_b64 v[0:1], 12, v[96:97]
	v_lshl_add_u64 v[0:1], v[18:19], 0, v[0:1]
	global_load_dwordx4 v[0:3], v[0:1], off nt
	v_lshl_add_u64 v[18:19], s[34:35], 1, v[10:11]
	v_lshlrev_b32_e32 v96, 11, v37
	v_or_b32_e32 v37, s6, v22
	v_lshl_add_u64 v[54:55], v[18:19], 0, v[96:97]
	v_lshlrev_b32_e32 v96, 11, v37
	v_or_b32_e32 v37, s6, v24
	s_waitcnt vmcnt(0)
	ds_write2_b32 v35, v0, v1 offset1:1
	ds_write2_b32 v35, v2, v3 offset0:2 offset1:3
	s_waitcnt lgkmcnt(0)
	ds_read2_b32 v[38:39], v36 offset0:33 offset1:41
	ds_read2_b32 v[40:41], v36 offset1:8
	ds_read2_b32 v[42:43], v36 offset0:66 offset1:74
	ds_read2_b32 v[44:45], v36 offset0:99 offset1:107
	ds_read2_b32 v[46:47], v36 offset0:132 offset1:140
	ds_read2_b32 v[48:49], v36 offset0:165 offset1:173
	ds_read2_b32 v[50:51], v36 offset0:198 offset1:206
	ds_read2_b32 v[52:53], v36 offset0:231 offset1:239
	s_waitcnt lgkmcnt(6)
	v_cvt_pk_bf16_f32 v0, v40, v38
	s_waitcnt lgkmcnt(4)
	v_cvt_pk_bf16_f32 v1, v42, v44
	s_waitcnt lgkmcnt(2)
	v_cvt_pk_bf16_f32 v2, v46, v48
	s_waitcnt lgkmcnt(0)
	v_cvt_pk_bf16_f32 v3, v50, v52
	global_store_dwordx4 v[54:55], v[0:3], off
	s_nop 1
	v_cvt_pk_bf16_f32 v0, v41, v39
	v_cvt_pk_bf16_f32 v1, v43, v45
	v_cvt_pk_bf16_f32 v2, v47, v49
	v_cvt_pk_bf16_f32 v3, v51, v53
	v_lshl_add_u64 v[38:39], v[18:19], 0, v[96:97]
	global_store_dwordx4 v[38:39], v[0:3], off
	ds_read2_b32 v[38:39], v36 offset0:49 offset1:57
	ds_read2_b32 v[40:41], v36 offset0:16 offset1:24
	ds_read2_b32 v[42:43], v36 offset0:82 offset1:90
	ds_read2_b32 v[44:45], v36 offset0:115 offset1:123
	ds_read2_b32 v[46:47], v36 offset0:148 offset1:156
	ds_read2_b32 v[48:49], v36 offset0:181 offset1:189
	ds_read2_b32 v[50:51], v36 offset0:214 offset1:222
	ds_read2_b32 v[52:53], v36 offset0:247 offset1:255
	v_lshlrev_b32_e32 v96, 11, v37
	v_or_b32_e32 v37, s6, v26
	s_waitcnt lgkmcnt(6)
	v_cvt_pk_bf16_f32 v0, v40, v38
	s_waitcnt lgkmcnt(4)
	v_cvt_pk_bf16_f32 v1, v42, v44
	s_waitcnt lgkmcnt(2)
	v_cvt_pk_bf16_f32 v2, v46, v48
	s_waitcnt lgkmcnt(0)
	v_cvt_pk_bf16_f32 v3, v50, v52
	v_lshl_add_u64 v[54:55], v[18:19], 0, v[96:97]
	v_lshlrev_b32_e32 v96, 11, v37
	global_store_dwordx4 v[54:55], v[0:3], off
	v_lshl_add_u64 v[18:19], v[18:19], 0, v[96:97]
	s_nop 0
	v_cvt_pk_bf16_f32 v0, v41, v39
	v_cvt_pk_bf16_f32 v1, v43, v45
	v_cvt_pk_bf16_f32 v2, v47, v49
	v_cvt_pk_bf16_f32 v3, v51, v53
	global_store_dwordx4 v[18:19], v[0:3], off
	s_waitcnt lgkmcnt(0)

; __device__ __forceinline__ unsigned pk_bf16(float lo, float hi) { return pg8::cvt_pk_bf16(lo, hi); }
; #define LDS_FENCE() asm volatile("s_waitcnt lgkmcnt(0)" ::: "memory")
; __device__ __forceinline__ void transpose_item(const float* Wsrc, int ldw, bf16_t* WT, int ldt, int kb, int nb, float* scr, int lane) {
;     const int k0 = 64 * kb, n0 = 32 * nb;
; #pragma unroll
;     for (int i = 0; i < 8; ++i) { const int kk = 8 * i + (lane >> 3), n4 = 4 * (lane & 7);
;         const f32x4 v = *(const f32x4*)(Wsrc + (size_t)(k0 + kk) * ldw + n0 + n4);
;         scr[kk * 33 + n4] = v[0]; scr[kk * 33 + n4 + 1] = v[1]; scr[kk * 33 + n4 + 2] = v[2]; scr[kk * 33 + n4 + 3] = v[3]; }
;     LDS_FENCE();
;     const int c = lane & 7;
; #pragma unroll
;     for (int j = 0; j < 4; ++j) { const int n = (lane >> 3) + 8 * j; const float* s = scr + (8 * c) * 33 + n;
;         u32x4 o; o.x = pk_bf16(s[0 * 33], s[1 * 33]); o.y = pk_bf16(s[2 * 33], s[3 * 33]); o.z = pk_bf16(s[4 * 33], s[5 * 33]); o.w = pk_bf16(s[6 * 33], s[7 * 33]);
;         *(u32x4*)(WT + (size_t)(n0 + n) * ldt + k0 + 8 * c) = o; }
;     LDS_FENCE();
; }
; __device__ __forceinline__ void phase_rows(const Ctx& c, int l) {
;     ...
;             if (r < I_B) { transpose_item(c.inp(IN_WUPB) + (size_t)l * 512 * 1024, 1024, Wup_t + 256, 1024, r / 32, r % 32, scr, lane); continue; } r -= I_B;
.LBB0_471:
	s_andn2_b64 vcc, exec, s[52:53]
	s_cbranch_vccnz .LBB0_473
	s_load_dwordx2 s[52:53], s[50:51], 0x80
	v_lshlrev_b32_e32 v96, 2, v4
	s_waitcnt lgkmcnt(0)
	s_add_u32 s31, s52, s48
	s_addc_u32 s36, s53, s49
	s_and_b32 s6, s21, 0x1fc0
	s_add_i32 s34, s6, 0xffffe700
	s_and_b32 s6, s13, 0x3e0
	s_lshl_b32 s47, s6, 2
	s_add_u32 s52, s31, s47
	s_addc_u32 s53, s36, 0
	v_lshl_add_u64 v[18:19], s[52:53], 0, v[96:97]
	v_or_b32_e32 v96, s34, v20
	v_lshlrev_b64 v[0:1], 12, v[96:97]
	v_lshl_add_u64 v[0:1], v[18:19], 0, v[0:1]
	global_load_dwordx4 v[0:3], v[0:1], off nt
	v_or_b32_e32 v96, s34, v22
	v_or_b32_e32 v37, s6, v20
	s_waitcnt vmcnt(0)
	ds_write2_b32 v21, v0, v1 offset1:1
	ds_write2_b32 v21, v2, v3 offset0:2 offset1:3
	v_lshlrev_b64 v[0:1], 12, v[96:97]
	v_lshl_add_u64 v[0:1], v[18:19], 0, v[0:1]
	global_load_dwordx4 v[0:3], v[0:1], off nt
	v_or_b32_e32 v96, s34, v24
	s_waitcnt vmcnt(0)
	ds_write2_b32 v23, v0, v1 offset1:1
	ds_write2_b32 v23, v2, v3 offset0:2 offset1:3
	v_lshlrev_b64 v[0:1], 12, v[96:97]
	v_lshl_add_u64 v[0:1], v[18:19], 0, v[0:1]
	global_load_dwordx4 v[0:3], v[0:1], off nt
	v_or_b32_e32 v96, s34, v26
	s_waitcnt vmcnt(0)
	ds_write2_b32 v25, v0, v1 offset1:1
	ds_write2_b32 v25, v2, v3 offset0:2 offset1:3
	v_lshlrev_b64 v[0:1], 12, v[96:97]
	v_lshl_add_u64 v[0:1], v[18:19], 0, v[0:1]
	global_load_dwordx4 v[0:3], v[0:1], off nt
	v_or_b32_e32 v96, s34, v28
	s_waitcnt vmcnt(0)
	ds_write2_b32 v27, v0, v1 offset1:1
	ds_write2_b32 v27, v2, v3 offset0:2 offset1:3
	v_lshlrev_b64 v[0:1], 12, v[96:97]
	v_lshl_add_u64 v[0:1], v[18:19], 0, v[0:1]
	global_load_dwordx4 v[0:3], v[0:1], off nt
	v_or_b32_e32 v96, s34, v30
	s_waitcnt vmcnt(0)
	ds_write2_b32 v29, v0, v1 offset1:1
	ds_write2_b32 v29, v2, v3 offset0:2 offset1:3
	v_lshlrev_b64 v[0:1], 12, v[96:97]
	v_lshl_add_u64 v[0:1], v[18:19], 0, v[0:1]
	global_load_dwordx4 v[0:3], v[0:1], off nt
	v_or_b32_e32 v96, s34, v32
	s_waitcnt vmcnt(0)
	ds_write2_b32 v31, v0, v1 offset1:1
	ds_write2_b32 v31, v2, v3 offset0:2 offset1:3
	v_lshlrev_b64 v[0:1], 12, v[96:97]
	v_lshl_add_u64 v[0:1], v[18:19], 0, v[0:1]
	global_load_dwordx4 v[0:3], v[0:1], off nt
	v_or_b32_e32 v96, s34, v34
	s_waitcnt vmcnt(0)
	ds_write2_b32 v33, v0, v1 offset1:1
	ds_write2_b32 v33, v2, v3 offset0:2 offset1:3
	v_lshlrev_b64 v[0:1], 12, v[96:97]
	v_lshl_add_u64 v[0:1], v[18:19], 0, v[0:1]
	global_load_dwordx4 v[0:3], v[0:1], off nt
	v_lshl_add_u64 v[18:19], s[34:35], 1, v[12:13]
	v_lshlrev_b32_e32 v96, 11, v37
	v_or_b32_e32 v37, s6, v22
	v_lshl_add_u64 v[54:55], v[18:19], 0, v[96:97]
	v_lshlrev_b32_e32 v96, 11, v37
	v_or_b32_e32 v37, s6, v24
	s_waitcnt vmcnt(0)
	ds_write2_b32 v35, v0, v1 offset1:1
	ds_write2_b32 v35, v2, v3 offset0:2 offset1:3
	s_waitcnt lgkmcnt(0)
	ds_read2_b32 v[38:39], v36 offset0:33 offset1:41
	ds_read2_b32 v[40:41], v36 offset1:8
	ds_read2_b32 v[42:43], v36 offset0:66 offset1:74
	ds_read2_b32 v[44:45], v36 offset0:99 offset1:107
	ds_read2_b32 v[46:47], v36 offset0:132 offset1:140
	ds_read2_b32 v[48:49], v36 offset0:165 offset1:173
	ds_read2_b32 v[50:51], v36 offset0:198 offset1:206
	ds_read2_b32 v[52:53], v36 offset0:231 offset1:239
	s_waitcnt lgkmcnt(6)
	v_cvt_pk_bf16_f32 v0, v40, v38
	s_waitcnt lgkmcnt(4)
	v_cvt_pk_bf16_f32 v1, v42, v44
	s_waitcnt lgkmcnt(2)
	v_cvt_pk_bf16_f32 v2, v46, v48
	s_waitcnt lgkmcnt(0)
	v_cvt_pk_bf16_f32 v3, v50, v52
	global_store_dwordx4 v[54:55], v[0:3], off
	s_nop 1
	v_cvt_pk_bf16_f32 v0, v41, v39
	v_cvt_pk_bf16_f32 v1, v43, v45
	v_cvt_pk_bf16_f32 v2, v47, v49
	v_cvt_pk_bf16_f32 v3, v51, v53
	v_lshl_add_u64 v[38:39], v[18:19], 0, v[96:97]
	global_store_dwordx4 v[38:39], v[0:3], off
	ds_read2_b32 v[38:39], v36 offset0:49 offset1:57
	ds_read2_b32 v[40:41], v36 offset0:16 offset1:24
	ds_read2_b32 v[42:43], v36 offset0:82 offset1:90
	ds_read2_b32 v[44:45], v36 offset0:115 offset1:123
	ds_read2_b32 v[46:47], v36 offset0:148 offset1:156
	ds_read2_b32 v[48:49], v36 offset0:181 offset1:189
	ds_read2_b32 v[50:51], v36 offset0:214 offset1:222
	ds_read2_b32 v[52:53], v36 offset0:247 offset1:255
	v_lshlrev_b32_e32 v96, 11, v37
	v_or_b32_e32 v37, s6, v26
	s_waitcnt lgkmcnt(6)
	v_cvt_pk_bf16_f32 v0, v40, v38
	s_waitcnt lgkmcnt(4)
	v_cvt_pk_bf16_f32 v1, v42, v44
	s_waitcnt lgkmcnt(2)
	v_cvt_pk_bf16_f32 v2, v46, v48
	s_waitcnt lgkmcnt(0)
	v_cvt_pk_bf16_f32 v3, v50, v52
	v_lshl_add_u64 v[54:55], v[18:19], 0, v[96:97]
	v_lshlrev_b32_e32 v96, 11, v37
	global_store_dwordx4 v[54:55], v[0:3], off
	v_lshl_add_u64 v[18:19], v[18:19], 0, v[96:97]
	s_nop 0
	v_cvt_pk_bf16_f32 v0, v41, v39
	v_cvt_pk_bf16_f32 v1, v43, v45
	v_cvt_pk_bf16_f32 v2, v47, v49
	v_cvt_pk_bf16_f32 v3, v51, v53
	global_store_dwordx4 v[18:19], v[0:3], off
	s_waitcnt lgkmcnt(0)

; __device__ __forceinline__ unsigned pk_bf16(float lo, float hi) { return pg8::cvt_pk_bf16(lo, hi); }
; #define LDS_FENCE() asm volatile("s_waitcnt lgkmcnt(0)" ::: "memory")
; __device__ __forceinline__ void transpose_item(const float* Wsrc, int ldw, bf16_t* WT, int ldt, int kb, int nb, float* scr, int lane) {
;     const int k0 = 64 * kb, n0 = 32 * nb;
; #pragma unroll
;     for (int i = 0; i < 8; ++i) { const int kk = 8 * i + (lane >> 3), n4 = 4 * (lane & 7);
;         const f32x4 v = *(const f32x4*)(Wsrc + (size_t)(k0 + kk) * ldw + n0 + n4);
;         scr[kk * 33 + n4] = v[0]; scr[kk * 33 + n4 + 1] = v[1]; scr[kk * 33 + n4 + 2] = v[2]; scr[kk * 33 + n4 + 3] = v[3]; }
;     LDS_FENCE();
;     const int c = lane & 7;
; #pragma unroll
;     for (int j = 0; j < 4; ++j) { const int n = (lane >> 3) + 8 * j; const float* s = scr + (8 * c) * 33 + n;
;         u32x4 o; o.x = pk_bf16(s[0 * 33], s[1 * 33]); o.y = pk_bf16(s[2 * 33], s[3 * 33]); o.z = pk_bf16(s[4 * 33], s[5 * 33]); o.w = pk_bf16(s[6 * 33], s[7 * 33]);
;         *(u32x4*)(WT + (size_t)(n0 + n) * ldt + k0 + 8 * c) = o; }
;     LDS_FENCE();
; }
; __device__ __forceinline__ void phase_rows(const Ctx& c, int l) {
;     ...
;             if (r < I_A) { transpose_item(c.inp(IN_WUPA) + (size_t)l * 256 * 1024, 1024, Wup_t, 1024, r / 32, r % 32, scr, lane); continue; } r -= I_A;
.LBB0_474:
	s_andn2_b64 vcc, exec, s[52:53]
	s_cbranch_vccnz .LBB0_476
	s_load_dwordx2 s[52:53], s[50:51], 0x78
	v_lshlrev_b32_e32 v96, 2, v4
	s_waitcnt lgkmcnt(0)
	s_add_u32 s31, s52, s42
	s_addc_u32 s36, s53, s43
	s_and_b32 s6, s21, 0x1fc0
	s_add_i32 s34, s6, 0xffffe800
	s_and_b32 s6, s13, 0x3e0
	s_lshl_b32 s47, s6, 2
	s_add_u32 s52, s31, s47
	s_addc_u32 s53, s36, 0
	v_lshl_add_u64 v[18:19], s[52:53], 0, v[96:97]
	v_or_b32_e32 v96, s34, v20
	v_lshlrev_b64 v[0:1], 12, v[96:97]
	v_lshl_add_u64 v[0:1], v[18:19], 0, v[0:1]
	global_load_dwordx4 v[0:3], v[0:1], off nt
	v_or_b32_e32 v96, s34, v22
	v_or_b32_e32 v37, s6, v20
	s_waitcnt vmcnt(0)
	ds_write2_b32 v21, v0, v1 offset1:1
	ds_write2_b32 v21, v2, v3 offset0:2 offset1:3
	v_lshlrev_b64 v[0:1], 12, v[96:97]
	v_lshl_add_u64 v[0:1], v[18:19], 0, v[0:1]
	global_load_dwordx4 v[0:3], v[0:1], off nt
	v_or_b32_e32 v96, s34, v24
	s_waitcnt vmcnt(0)
	ds_write2_b32 v23, v0, v1 offset1:1
	ds_write2_b32 v23, v2, v3 offset0:2 offset1:3
	v_lshlrev_b64 v[0:1], 12, v[96:97]
	v_lshl_add_u64 v[0:1], v[18:19], 0, v[0:1]
	global_load_dwordx4 v[0:3], v[0:1], off nt
	v_or_b32_e32 v96, s34, v26
	s_waitcnt vmcnt(0)
	ds_write2_b32 v25, v0, v1 offset1:1
	ds_write2_b32 v25, v2, v3 offset0:2 offset1:3
	v_lshlrev_b64 v[0:1], 12, v[96:97]
	v_lshl_add_u64 v[0:1], v[18:19], 0, v[0:1]
	global_load_dwordx4 v[0:3], v[0:1], off nt
	v_or_b32_e32 v96, s34, v28
	s_waitcnt vmcnt(0)
	ds_write2_b32 v27, v0, v1 offset1:1
	ds_write2_b32 v27, v2, v3 offset0:2 offset1:3
	v_lshlrev_b64 v[0:1], 12, v[96:97]
	v_lshl_add_u64 v[0:1], v[18:19], 0, v[0:1]
	global_load_dwordx4 v[0:3], v[0:1], off nt
	v_or_b32_e32 v96, s34, v30
	s_waitcnt vmcnt(0)
	ds_write2_b32 v29, v0, v1 offset1:1
	ds_write2_b32 v29, v2, v3 offset0:2 offset1:3
	v_lshlrev_b64 v[0:1], 12, v[96:97]
	v_lshl_add_u64 v[0:1], v[18:19], 0, v[0:1]
	global_load_dwordx4 v[0:3], v[0:1], off nt
	v_or_b32_e32 v96, s34, v32
	s_waitcnt vmcnt(0)
	ds_write2_b32 v31, v0, v1 offset1:1
	ds_write2_b32 v31, v2, v3 offset0:2 offset1:3
	v_lshlrev_b64 v[0:1], 12, v[96:97]
	v_lshl_add_u64 v[0:1], v[18:19], 0, v[0:1]
	global_load_dwordx4 v[0:3], v[0:1], off nt
	v_or_b32_e32 v96, s34, v34
	s_waitcnt vmcnt(0)
	ds_write2_b32 v33, v0, v1 offset1:1
	ds_write2_b32 v33, v2, v3 offset0:2 offset1:3
	v_lshlrev_b64 v[0:1], 12, v[96:97]
	v_lshl_add_u64 v[0:1], v[18:19], 0, v[0:1]
	global_load_dwordx4 v[0:3], v[0:1], off nt
	v_lshl_add_u64 v[18:19], s[34:35], 1, v[14:15]
	v_lshlrev_b32_e32 v96, 11, v37
	v_or_b32_e32 v37, s6, v22
	v_lshl_add_u64 v[54:55], v[18:19], 0, v[96:97]
	v_lshlrev_b32_e32 v96, 11, v37
	v_or_b32_e32 v37, s6, v24
	s_waitcnt vmcnt(0)
	ds_write2_b32 v35, v0, v1 offset1:1
	ds_write2_b32 v35, v2, v3 offset0:2 offset1:3
	s_waitcnt lgkmcnt(0)
	ds_read2_b32 v[38:39], v36 offset0:33 offset1:41
	ds_read2_b32 v[40:41], v36 offset1:8
	ds_read2_b32 v[42:43], v36 offset0:66 offset1:74
	ds_read2_b32 v[44:45], v36 offset0:99 offset1:107
	ds_read2_b32 v[46:47], v36 offset0:132 offset1:140
	ds_read2_b32 v[48:49], v36 offset0:165 offset1:173
	ds_read2_b32 v[50:51], v36 offset0:198 offset1:206
	ds_read2_b32 v[52:53], v36 offset0:231 offset1:239
	s_waitcnt lgkmcnt(6)
	v_cvt_pk_bf16_f32 v0, v40, v38
	s_waitcnt lgkmcnt(4)
	v_cvt_pk_bf16_f32 v1, v42, v44
	s_waitcnt lgkmcnt(2)
	v_cvt_pk_bf16_f32 v2, v46, v48
	s_waitcnt lgkmcnt(0)
	v_cvt_pk_bf16_f32 v3, v50, v52
	global_store_dwordx4 v[54:55], v[0:3], off
	s_nop 1
	v_cvt_pk_bf16_f32 v0, v41, v39
	v_cvt_pk_bf16_f32 v1, v43, v45
	v_cvt_pk_bf16_f32 v2, v47, v49
	v_cvt_pk_bf16_f32 v3, v51, v53
	v_lshl_add_u64 v[38:39], v[18:19], 0, v[96:97]
	global_store_dwordx4 v[38:39], v[0:3], off
	ds_read2_b32 v[38:39], v36 offset0:49 offset1:57
	ds_read2_b32 v[40:41], v36 offset0:16 offset1:24
	ds_read2_b32 v[42:43], v36 offset0:82 offset1:90
	ds_read2_b32 v[44:45], v36 offset0:115 offset1:123
	ds_read2_b32 v[46:47], v36 offset0:148 offset1:156
	ds_read2_b32 v[48:49], v36 offset0:181 offset1:189
	ds_read2_b32 v[50:51], v36 offset0:214 offset1:222
	ds_read2_b32 v[52:53], v36 offset0:247 offset1:255
	v_lshlrev_b32_e32 v96, 11, v37
	v_or_b32_e32 v37, s6, v26
	s_waitcnt lgkmcnt(6)
	v_cvt_pk_bf16_f32 v0, v40, v38
	s_waitcnt lgkmcnt(4)
	v_cvt_pk_bf16_f32 v1, v42, v44
	s_waitcnt lgkmcnt(2)
	v_cvt_pk_bf16_f32 v2, v46, v48
	s_waitcnt lgkmcnt(0)
	v_cvt_pk_bf16_f32 v3, v50, v52
	v_lshl_add_u64 v[54:55], v[18:19], 0, v[96:97]
	v_lshlrev_b32_e32 v96, 11, v37
	global_store_dwordx4 v[54:55], v[0:3], off
	v_lshl_add_u64 v[18:19], v[18:19], 0, v[96:97]
	s_nop 0
	v_cvt_pk_bf16_f32 v0, v41, v39
	v_cvt_pk_bf16_f32 v1, v43, v45
	v_cvt_pk_bf16_f32 v2, v47, v49
	v_cvt_pk_bf16_f32 v3, v51, v53
	global_store_dwordx4 v[18:19], v[0:3], off
	s_waitcnt lgkmcnt(0)

; __device__ __forceinline__ unsigned pk_bf16(float lo, float hi) { return pg8::cvt_pk_bf16(lo, hi); }
; #define LDS_FENCE() asm volatile("s_waitcnt lgkmcnt(0)" ::: "memory")
; __device__ __forceinline__ void transpose_item(const float* Wsrc, int ldw, bf16_t* WT, int ldt, int kb, int nb, float* scr, int lane) {
;     const int k0 = 64 * kb, n0 = 32 * nb;
; #pragma unroll
;     for (int i = 0; i < 8; ++i) { const int kk = 8 * i + (lane >> 3), n4 = 4 * (lane & 7);
;         const f32x4 v = *(const f32x4*)(Wsrc + (size_t)(k0 + kk) * ldw + n0 + n4);
;         scr[kk * 33 + n4] = v[0]; scr[kk * 33 + n4 + 1] = v[1]; scr[kk * 33 + n4 + 2] = v[2]; scr[kk * 33 + n4 + 3] = v[3]; }
;     LDS_FENCE();
;     const int c = lane & 7;
; #pragma unroll
;     for (int j = 0; j < 4; ++j) { const int n = (lane >> 3) + 8 * j; const float* s = scr + (8 * c) * 33 + n;
;         u32x4 o; o.x = pk_bf16(s[0 * 33], s[1 * 33]); o.y = pk_bf16(s[2 * 33], s[3 * 33]); o.z = pk_bf16(s[4 * 33], s[5 * 33]); o.w = pk_bf16(s[6 * 33], s[7 * 33]);
;         *(u32x4*)(WT + (size_t)(n0 + n) * ldt + k0 + 8 * c) = o; }
;     LDS_FENCE();
; }
; __device__ __forceinline__ void phase_rows(const Ctx& c, int l) {
;     ...
;             if (r < I_IN) { const int kb = r / 192, nb = r % 192; const float* src = c.inp(IN_WIN) + (size_t)l * 1024 * DIN + (nb >= 64 ? 8 : 0);
;                 transpose_item(src, DIN, Win_t, 1024, kb, nb, scr, lane); continue; } r -= I_IN;
.LBB0_477:
	s_andn2_b64 vcc, exec, s[52:53]
	s_cbranch_vccnz .LBB0_458
	s_mul_hi_i32 s6, s23, 0x2aaaaaab
	s_load_dwordx2 s[52:53], s[50:51], 0x8
	s_lshr_b32 s31, s6, 31
	s_ashr_i32 s6, s6, 5
	s_add_i32 s6, s6, s31
	s_mul_i32 s31, s6, 0xffffff40
	s_add_i32 s31, s23, s31
	s_waitcnt lgkmcnt(0)
	s_add_u32 s34, s52, s12
	s_addc_u32 s36, s53, s0
	s_cmp_gt_i32 s31, 63
	s_cselect_b32 s31, 32, 0
	s_add_u32 s31, s34, s31
	s_addc_u32 s34, s36, 0
	s_lshl_b32 s54, s6, 6
	s_mulk_i32 s6, 0xe800
	s_add_i32 s52, s13, s6
	s_ashr_i32 s53, s52, 31
	s_lshl_b64 s[60:61], s[52:53], 2
	s_add_u32 s60, s31, s60
	s_addc_u32 s61, s34, s61
	v_lshlrev_b32_e32 v96, 2, v4
	v_lshl_add_u64 v[18:19], s[60:61], 0, v[96:97]
	v_or_b32_e32 v0, s54, v20
	s_movk_i32 s6, 0x6020
	v_mad_i64_i32 v[0:1], s[60:61], v0, s6, v[18:19]
	global_load_dwordx4 v[0:3], v[0:1], off nt
	s_ashr_i32 s55, s54, 31
	s_waitcnt vmcnt(0)
	ds_write2_b32 v21, v0, v1 offset1:1
	ds_write2_b32 v21, v2, v3 offset0:2 offset1:3
	v_or_b32_e32 v0, s54, v22
	v_mad_i64_i32 v[0:1], s[60:61], v0, s6, v[18:19]
	global_load_dwordx4 v[0:3], v[0:1], off nt
	s_waitcnt vmcnt(0)
	ds_write2_b32 v23, v0, v1 offset1:1
	ds_write2_b32 v23, v2, v3 offset0:2 offset1:3
	v_or_b32_e32 v0, s54, v24
	v_mad_i64_i32 v[0:1], s[60:61], v0, s6, v[18:19]
	global_load_dwordx4 v[0:3], v[0:1], off nt
	s_waitcnt vmcnt(0)
	ds_write2_b32 v25, v0, v1 offset1:1
	ds_write2_b32 v25, v2, v3 offset0:2 offset1:3
	v_or_b32_e32 v0, s54, v26
	v_mad_i64_i32 v[0:1], s[60:61], v0, s6, v[18:19]
	global_load_dwordx4 v[0:3], v[0:1], off nt
	s_waitcnt vmcnt(0)
	ds_write2_b32 v27, v0, v1 offset1:1
	ds_write2_b32 v27, v2, v3 offset0:2 offset1:3
	v_or_b32_e32 v0, s54, v28
	v_mad_i64_i32 v[0:1], s[60:61], v0, s6, v[18:19]
	global_load_dwordx4 v[0:3], v[0:1], off nt
	s_waitcnt vmcnt(0)
	ds_write2_b32 v29, v0, v1 offset1:1
	ds_write2_b32 v29, v2, v3 offset0:2 offset1:3
	v_or_b32_e32 v0, s54, v30
	v_mad_i64_i32 v[0:1], s[60:61], v0, s6, v[18:19]
	global_load_dwordx4 v[0:3], v[0:1], off nt
	s_waitcnt vmcnt(0)
	ds_write2_b32 v31, v0, v1 offset1:1
	ds_write2_b32 v31, v2, v3 offset0:2 offset1:3
	v_or_b32_e32 v0, s54, v32
	v_mad_i64_i32 v[0:1], s[60:61], v0, s6, v[18:19]
	global_load_dwordx4 v[0:3], v[0:1], off nt
	s_waitcnt vmcnt(0)
	ds_write2_b32 v33, v0, v1 offset1:1
	ds_write2_b32 v33, v2, v3 offset0:2 offset1:3
	v_or_b32_e32 v0, s54, v34
	v_mad_i64_i32 v[0:1], s[60:61], v0, s6, v[18:19]
	global_load_dwordx4 v[0:3], v[0:1], off nt
	s_waitcnt vmcnt(0)
	ds_write2_b32 v35, v0, v1 offset1:1
	ds_write2_b32 v35, v2, v3 offset0:2 offset1:3
	s_waitcnt lgkmcnt(0)
	ds_read2_b32 v[18:19], v36 offset0:33 offset1:41
	ds_read2_b32 v[42:43], v36 offset1:8
	ds_read2_b32 v[44:45], v36 offset0:66 offset1:74
	ds_read2_b32 v[46:47], v36 offset0:99 offset1:107
	ds_read2_b32 v[48:49], v36 offset0:132 offset1:140
	ds_read2_b32 v[50:51], v36 offset0:165 offset1:173
	ds_read2_b32 v[52:53], v36 offset0:198 offset1:206
	ds_read2_b32 v[54:55], v36 offset0:231 offset1:239
	v_add_u32_e32 v2, s52, v20
	v_ashrrev_i32_e32 v3, 31, v2
	v_lshl_add_u64 v[0:1], s[54:55], 1, v[16:17]
	v_lshlrev_b64 v[56:57], 11, v[2:3]
	s_waitcnt lgkmcnt(6)
	v_cvt_pk_bf16_f32 v38, v42, v18
	s_waitcnt lgkmcnt(4)
	v_cvt_pk_bf16_f32 v39, v44, v46
	s_waitcnt lgkmcnt(2)
	v_cvt_pk_bf16_f32 v40, v48, v50
	s_waitcnt lgkmcnt(0)
	v_cvt_pk_bf16_f32 v41, v52, v54
	v_lshl_add_u64 v[56:57], v[0:1], 0, v[56:57]
	v_add_u32_e32 v18, 8, v2
	global_store_dwordx4 v[56:57], v[38:41], off
	v_add_u32_e32 v56, 16, v2
	v_ashrrev_i32_e32 v57, 31, v56
	v_cvt_pk_bf16_f32 v38, v43, v19
	v_ashrrev_i32_e32 v19, 31, v18
	v_lshlrev_b64 v[18:19], 11, v[18:19]
	v_cvt_pk_bf16_f32 v39, v45, v47
	v_cvt_pk_bf16_f32 v40, v49, v51
	v_cvt_pk_bf16_f32 v41, v53, v55
	v_lshl_add_u64 v[18:19], v[0:1], 0, v[18:19]
	global_store_dwordx4 v[18:19], v[38:41], off
	ds_read2_b32 v[18:19], v36 offset0:49 offset1:57
	ds_read2_b32 v[42:43], v36 offset0:16 offset1:24
	ds_read2_b32 v[44:45], v36 offset0:82 offset1:90
	ds_read2_b32 v[46:47], v36 offset0:115 offset1:123
	ds_read2_b32 v[48:49], v36 offset0:148 offset1:156
	ds_read2_b32 v[50:51], v36 offset0:181 offset1:189
	ds_read2_b32 v[52:53], v36 offset0:214 offset1:222
	ds_read2_b32 v[54:55], v36 offset0:247 offset1:255
	v_add_u32_e32 v2, 24, v2
	v_lshlrev_b64 v[56:57], 11, v[56:57]
	v_ashrrev_i32_e32 v3, 31, v2
	s_waitcnt lgkmcnt(6)
	v_cvt_pk_bf16_f32 v38, v42, v18
	s_waitcnt lgkmcnt(4)
	v_cvt_pk_bf16_f32 v39, v44, v46
	s_waitcnt lgkmcnt(2)
	v_cvt_pk_bf16_f32 v40, v48, v50
	s_waitcnt lgkmcnt(0)
	v_cvt_pk_bf16_f32 v41, v52, v54
	v_lshl_add_u64 v[56:57], v[0:1], 0, v[56:57]
	v_lshlrev_b64 v[2:3], 11, v[2:3]
	global_store_dwordx4 v[56:57], v[38:41], off
	v_lshl_add_u64 v[0:1], v[0:1], 0, v[2:3]
	s_nop 0
	v_cvt_pk_bf16_f32 v38, v43, v19
	v_cvt_pk_bf16_f32 v39, v45, v47
	v_cvt_pk_bf16_f32 v40, v49, v51
	v_cvt_pk_bf16_f32 v41, v53, v55
	global_store_dwordx4 v[0:1], v[38:41], off
	s_waitcnt lgkmcnt(0)
	s_branch .LBB0_458
